# v049 + next-layer norm gain/scale/shift vectors fetched in two batched round trips instead of eight serialized ones
# speedup vs baseline: 1.0014x; 1.0014x over previous
.LBB0_110:
	v_bfe_u32 v154, v160, v182, 8
	s_waitcnt lgkmcnt(7)
	v_mov_b32_e32 v196, v137
	v_mov_b32_e32 v198, v136
	v_lshlrev_b64 v[136:137], v132, v[154:155]
	s_barrier
	s_add_i32 s14, s14, 2
	s_waitcnt vmcnt(11)
	v_mfma_f32_16x16x32_fp8_fp8 v[122:125], v[136:137], v[42:43], v[122:125]
	v_lshlrev_b32_e32 v42, 10, v198
	v_and_b32_e32 v154, 0x3fffc00, v42
	v_lshl_add_u64 v[42:43], v[140:141], 0, v[154:155]
	v_mfma_f32_16x16x32_fp8_fp8 v[126:129], v[136:137], v[44:45], v[126:129]
	global_load_dwordx4 v[42:45], v[42:43], off
	s_min_u32 s15, s14, 27
	s_add_i32 s18, s15, 4
	s_sub_i32 s15, 27, s15
	s_and_b64 s[16:17], s[12:13], exec
	s_cselect_b32 s15, s15, s18
	s_waitcnt lgkmcnt(4)
	v_mov_b32_e32 v184, v167
	v_lshl_add_u32 v167, s15, 4, v183
	ds_read_b32 v136, v167 offset:512
	s_waitcnt lgkmcnt(1)
	v_mov_b32_e32 v1, v175
	v_mov_b32_e32 v185, v174
	v_mov_b32_e32 v186, v166
	v_mov_b32_e32 v187, v173
	v_mov_b32_e32 v188, v165
	v_mov_b32_e32 v189, v172
	v_mov_b32_e32 v190, v164
	v_mov_b32_e32 v191, v171
	v_mov_b32_e32 v192, v163
	v_mov_b32_e32 v193, v170
	v_mov_b32_e32 v194, v162
	v_mov_b32_e32 v195, v169
	v_mov_b32_e32 v197, v168
	v_bfe_u32 v154, v161, v182, 8
	v_lshlrev_b64 v[160:161], v132, v[154:155]
	ds_read_b32 v137, v167 offset:2048
	s_waitcnt vmcnt(11)
	v_mfma_f32_16x16x32_fp8_fp8 v[114:117], v[160:161], v[46:47], v[114:117]
	v_lshlrev_b32_e32 v46, 10, v196
	v_and_b32_e32 v154, 0x3fffc00, v46
	v_lshl_add_u64 v[46:47], v[140:141], 0, v[154:155]
	v_mfma_f32_16x16x32_fp8_fp8 v[118:121], v[160:161], v[48:49], v[118:121]
	global_load_dwordx4 v[46:49], v[46:47], off
	v_bfe_u32 v154, v152, v182, 8
	v_lshlrev_b64 v[160:161], v132, v[154:155]
	ds_read_b32 v162, v167 offset:3584
	s_waitcnt vmcnt(11)
	v_mfma_f32_16x16x32_fp8_fp8 v[82:85], v[160:161], v[50:51], v[82:85]
	v_lshlrev_b32_e32 v50, 10, v194
	v_and_b32_e32 v154, 0x3fffc00, v50
	v_lshl_add_u64 v[50:51], v[140:141], 0, v[154:155]
	v_mfma_f32_16x16x32_fp8_fp8 v[86:89], v[160:161], v[52:53], v[86:89]
	global_load_dwordx4 v[50:53], v[50:51], off
	v_bfe_u32 v154, v153, v182, 8
	v_lshlrev_b64 v[152:153], v132, v[154:155]
	ds_read_b32 v163, v167 offset:5120
	s_waitcnt vmcnt(11)
	v_mfma_f32_16x16x32_fp8_fp8 v[34:37], v[152:153], v[54:55], v[34:37]
	v_lshlrev_b32_e32 v54, 10, v192
	v_and_b32_e32 v154, 0x3fffc00, v54
	v_lshl_add_u64 v[54:55], v[140:141], 0, v[154:155]
	v_mfma_f32_16x16x32_fp8_fp8 v[38:41], v[152:153], v[56:57], v[38:41]
	global_load_dwordx4 v[54:57], v[54:55], off
	v_bfe_u32 v154, v150, v182, 8
	v_lshlrev_b64 v[152:153], v132, v[154:155]
	ds_read_b32 v164, v167 offset:6656
	s_waitcnt vmcnt(11)
	v_mfma_f32_16x16x32_fp8_fp8 v[26:29], v[152:153], v[58:59], v[26:29]
	v_lshlrev_b32_e32 v58, 10, v190
	v_and_b32_e32 v154, 0x3fffc00, v58
	v_lshl_add_u64 v[58:59], v[140:141], 0, v[154:155]
	v_mfma_f32_16x16x32_fp8_fp8 v[30:33], v[152:153], v[60:61], v[30:33]
	global_load_dwordx4 v[58:61], v[58:59], off
	v_bfe_u32 v154, v151, v182, 8
	v_lshlrev_b64 v[150:151], v132, v[154:155]
	ds_read_b32 v165, v167 offset:8192
	s_waitcnt vmcnt(11)
	v_mfma_f32_16x16x32_fp8_fp8 v[18:21], v[150:151], v[62:63], v[18:21]
	v_lshlrev_b32_e32 v62, 10, v188
	v_and_b32_e32 v154, 0x3fffc00, v62
	v_lshl_add_u64 v[62:63], v[140:141], 0, v[154:155]
	v_mfma_f32_16x16x32_fp8_fp8 v[22:25], v[150:151], v[64:65], v[22:25]
	global_load_dwordx4 v[62:65], v[62:63], off
	v_bfe_u32 v154, v148, v182, 8
	v_lshlrev_b64 v[150:151], v132, v[154:155]
	ds_read_b32 v166, v167 offset:9728
	s_waitcnt vmcnt(11)
	v_mfma_f32_16x16x32_fp8_fp8 v[10:13], v[150:151], v[66:67], v[10:13]
	v_lshlrev_b32_e32 v66, 10, v186
	v_and_b32_e32 v154, 0x3fffc00, v66
	v_lshl_add_u64 v[66:67], v[140:141], 0, v[154:155]
	v_mfma_f32_16x16x32_fp8_fp8 v[14:17], v[150:151], v[68:69], v[14:17]
	global_load_dwordx4 v[66:69], v[66:67], off
	v_bfe_u32 v154, v149, v182, 8
	v_lshlrev_b64 v[148:149], v132, v[154:155]
	ds_read_b32 v167, v167 offset:11264
	s_waitcnt vmcnt(11)
	v_mfma_f32_16x16x32_fp8_fp8 v[2:5], v[148:149], v[70:71], v[2:5]
	v_lshlrev_b32_e32 v70, 10, v184
	v_and_b32_e32 v154, 0x3fffc00, v70
	v_lshl_add_u64 v[70:71], v[140:141], 0, v[154:155]
	v_mfma_f32_16x16x32_fp8_fp8 v[6:9], v[148:149], v[72:73], v[6:9]
	global_load_dwordx4 v[70:73], v[70:71], off
	v_bfe_u32 v154, v146, v182, 8
	v_lshlrev_b64 v[148:149], v132, v[154:155]
	s_min_u32 s15, s14, 26
	s_add_i32 s18, s15, 5
	s_sub_i32 s15, 26, s15
	s_and_b64 s[16:17], s[12:13], exec
	s_waitcnt vmcnt(11)
	v_mfma_f32_16x16x32_fp8_fp8 v[122:125], v[148:149], v[74:75], v[122:125]
	v_lshlrev_b32_e32 v74, 10, v197
	v_and_b32_e32 v154, 0x3fffc00, v74
	v_lshl_add_u64 v[74:75], v[140:141], 0, v[154:155]
	v_mfma_f32_16x16x32_fp8_fp8 v[126:129], v[148:149], v[76:77], v[126:129]
	global_load_dwordx4 v[74:77], v[74:75], off
	s_cselect_b32 s15, s15, s18
	v_lshl_add_u32 v148, s15, 4, v183
	ds_read_b32 v168, v148 offset:512
	v_bfe_u32 v154, v147, v182, 8
	v_lshlrev_b64 v[146:147], v132, v[154:155]
	ds_read_b32 v169, v148 offset:2048
	s_waitcnt vmcnt(11)
	v_mfma_f32_16x16x32_fp8_fp8 v[114:117], v[146:147], v[78:79], v[114:117]
	v_lshlrev_b32_e32 v78, 10, v195
	v_and_b32_e32 v154, 0x3fffc00, v78
	v_lshl_add_u64 v[78:79], v[140:141], 0, v[154:155]
	v_mfma_f32_16x16x32_fp8_fp8 v[118:121], v[146:147], v[80:81], v[118:121]
	global_load_dwordx4 v[78:81], v[78:79], off
	v_bfe_u32 v154, v144, v182, 8
	v_lshlrev_b64 v[146:147], v132, v[154:155]
	ds_read_b32 v170, v148 offset:3584
	s_waitcnt vmcnt(11)
	v_mfma_f32_16x16x32_fp8_fp8 v[82:85], v[146:147], v[90:91], v[82:85]
	v_lshlrev_b32_e32 v90, 10, v193
	v_and_b32_e32 v154, 0x3fffc00, v90
	v_lshl_add_u64 v[90:91], v[140:141], 0, v[154:155]
	v_mfma_f32_16x16x32_fp8_fp8 v[86:89], v[146:147], v[92:93], v[86:89]
	global_load_dwordx4 v[90:93], v[90:91], off
	v_bfe_u32 v154, v145, v182, 8
	v_lshlrev_b64 v[144:145], v132, v[154:155]
	ds_read_b32 v171, v148 offset:5120
	s_waitcnt vmcnt(11)
	v_mfma_f32_16x16x32_fp8_fp8 v[34:37], v[144:145], v[94:95], v[34:37]
	v_lshlrev_b32_e32 v94, 10, v191
	v_and_b32_e32 v154, 0x3fffc00, v94
	v_lshl_add_u64 v[94:95], v[140:141], 0, v[154:155]
	v_mfma_f32_16x16x32_fp8_fp8 v[38:41], v[144:145], v[96:97], v[38:41]
	global_load_dwordx4 v[94:97], v[94:95], off
	v_bfe_u32 v154, v142, v182, 8
	v_lshlrev_b64 v[144:145], v132, v[154:155]
	ds_read_b32 v172, v148 offset:6656
	s_waitcnt vmcnt(11)
	v_mfma_f32_16x16x32_fp8_fp8 v[26:29], v[144:145], v[98:99], v[26:29]
	v_lshlrev_b32_e32 v98, 10, v189
	v_and_b32_e32 v154, 0x3fffc00, v98
	v_lshl_add_u64 v[98:99], v[140:141], 0, v[154:155]
	v_mfma_f32_16x16x32_fp8_fp8 v[30:33], v[144:145], v[100:101], v[30:33]
	global_load_dwordx4 v[98:101], v[98:99], off
	v_bfe_u32 v154, v143, v182, 8
	v_lshlrev_b64 v[142:143], v132, v[154:155]
	ds_read_b32 v173, v148 offset:8192
	s_waitcnt vmcnt(11)
	v_mfma_f32_16x16x32_fp8_fp8 v[18:21], v[142:143], v[102:103], v[18:21]
	v_lshlrev_b32_e32 v102, 10, v187
	v_and_b32_e32 v154, 0x3fffc00, v102
	v_lshl_add_u64 v[102:103], v[140:141], 0, v[154:155]
	v_mfma_f32_16x16x32_fp8_fp8 v[22:25], v[142:143], v[104:105], v[22:25]
	global_load_dwordx4 v[102:105], v[102:103], off
	v_bfe_u32 v154, v138, v182, 8
	v_lshlrev_b64 v[142:143], v132, v[154:155]
	ds_read_b32 v174, v148 offset:9728
	s_waitcnt vmcnt(11)
	v_mfma_f32_16x16x32_fp8_fp8 v[10:13], v[142:143], v[106:107], v[10:13]
	v_lshlrev_b32_e32 v106, 10, v185
	v_and_b32_e32 v154, 0x3fffc00, v106
	v_lshl_add_u64 v[106:107], v[140:141], 0, v[154:155]
	v_mfma_f32_16x16x32_fp8_fp8 v[14:17], v[142:143], v[108:109], v[14:17]
	global_load_dwordx4 v[106:109], v[106:107], off
	v_bfe_u32 v154, v139, v182, 8
	v_lshlrev_b64 v[138:139], v132, v[154:155]
	ds_read_b32 v175, v148 offset:11264
	s_waitcnt vmcnt(11)
	v_mfma_f32_16x16x32_fp8_fp8 v[2:5], v[138:139], v[110:111], v[2:5]
	v_lshlrev_b32_e32 v110, 10, v1
	v_and_b32_e32 v154, 0x3fffc00, v110
	v_lshl_add_u64 v[110:111], v[140:141], 0, v[154:155]
	v_mfma_f32_16x16x32_fp8_fp8 v[6:9], v[138:139], v[112:113], v[6:9]
	global_load_dwordx4 v[110:113], v[110:111], off
	s_cmp_gt_u32 s14, 29
	v_mov_b32_e32 v160, v198
	v_mov_b32_e32 v146, v197
	v_mov_b32_e32 v161, v196
	v_mov_b32_e32 v147, v195
	v_mov_b32_e32 v152, v194
	v_mov_b32_e32 v144, v193
	v_mov_b32_e32 v153, v192
	v_mov_b32_e32 v145, v191
	v_mov_b32_e32 v150, v190
	v_mov_b32_e32 v142, v189
	v_mov_b32_e32 v151, v188
	v_mov_b32_e32 v143, v187
	v_mov_b32_e32 v148, v186
	v_mov_b32_e32 v138, v185
	v_mov_b32_e32 v149, v184
	v_mov_b32_e32 v139, v1
	s_cbranch_scc0 .LBB0_110
	v_mov_b32_e32 v1, v176
	s_add_i32 s10, s10, 1
	s_waitcnt vmcnt(15)
	v_lshlrev_b32_e32 v42, 4, v1
	v_ashrrev_i32_e32 v43, 2, v1
	v_and_b32_e32 v42, 0xf0, v42
	v_and_b32_e32 v43, -8, v43
	v_add_u32_e32 v42, v42, v43
	v_lshrrev_b32_e32 v1, 2, v1
	s_waitcnt vmcnt(14)
	v_and_or_b32 v46, v1, 4, v42
	v_ashrrev_i32_e32 v47, 31, v46
	v_lshl_add_u64 v[42:43], v[46:47], 2, s[0:1]
	v_lshl_add_u64 v[42:43], s[60:61], 2, v[42:43]
	v_lshl_add_u64 v[46:47], v[46:47], 1, s[22:23]
	s_lshl_b32 s60, s60, 1
	v_lshl_add_u64 v[46:47], v[46:47], 0, s[60:61]
	s_waitcnt vmcnt(7)
	v_lshl_add_u64 v[74:75], v[46:47], 0, s[38:39]
	s_waitcnt vmcnt(0)
	v_mov_b32_e32 v76, v228
	v_mov_b32_e32 v77, v229
	v_lshl_add_u64 v[70:71], v[46:47], 0, s[42:43]
	v_mov_b32_e32 v42, v244
	v_mov_b32_e32 v43, v245
	v_mov_b32_e32 v44, v246
	v_mov_b32_e32 v45, v247
	v_lshl_add_u64 v[66:67], v[46:47], 0, s[46:47]
	v_mov_b32_e32 v72, v230
	v_mov_b32_e32 v73, v231
	v_mov_b32_e32 v68, v232
	v_mov_b32_e32 v69, v233
	v_lshl_add_u64 v[62:63], v[46:47], 0, s[50:51]
	v_mov_b32_e32 v64, v234
	v_mov_b32_e32 v65, v235
	v_lshl_add_u64 v[58:59], v[46:47], 0, s[54:55]
	v_mov_b32_e32 v60, v236
	v_mov_b32_e32 v61, v237
	v_lshl_add_u64 v[54:55], v[46:47], 0, s[58:59]
	v_mov_b32_e32 v56, v238
	v_mov_b32_e32 v57, v239
	v_lshl_add_u64 v[50:51], v[46:47], 0, s[64:65]
	v_mov_b32_e32 v52, v240
	v_mov_b32_e32 v53, v241
	v_lshl_add_u64 v[46:47], v[46:47], 0, s[68:69]
	v_mov_b32_e32 v48, v242
	v_mov_b32_e32 v49, v243
	v_mov_b32_e32 v1, s93
	s_waitcnt vmcnt(15)
	ds_read_b32 v78, v1 offset:14336
	s_nop 1
	v_permlane32_swap_b32 v122, v126
	s_nop 1
	v_permlane32_swap_b32 v123, v127
	s_nop 1
	v_permlane32_swap_b32 v124, v128
	s_nop 1
	v_permlane32_swap_b32 v125, v129
	s_cmp_eq_u32 s10, 4
	v_pk_add_f32 v[80:81], v[122:123], v[126:127]
	s_waitcnt vmcnt(14)
	v_pk_add_f32 v[90:91], v[124:125], v[128:129]
	s_waitcnt lgkmcnt(0)
	v_pk_mul_f32 v[80:81], v[78:79], v[80:81] op_sel_hi:[0,1]
	v_pk_mul_f32 v[78:79], v[78:79], v[90:91] op_sel_hi:[0,1]
	s_waitcnt vmcnt(8)
	v_lshlrev_b32_e32 v90, 16, v76
	v_and_b32_e32 v91, 0xffff0000, v76
	v_lshlrev_b32_e32 v76, 16, v77
	v_and_b32_e32 v77, 0xffff0000, v77
	s_waitcnt vmcnt(7)
	v_pk_fma_f32 v[76:77], v[44:45], v[78:79], v[76:77]
	v_pk_fma_f32 v[78:79], v[42:43], v[80:81], v[90:91]
	s_nop 0
	v_cvt_pk_bf16_f32 v78, v78, v79
	v_cvt_pk_bf16_f32 v79, v76, v77
	global_store_dwordx2 v[74:75], v[78:79], off
	ds_read_b32 v74, v1 offset:14340
	s_nop 1
	v_permlane32_swap_b32 v114, v118
	s_nop 1
	v_permlane32_swap_b32 v115, v119
	s_nop 1
	v_permlane32_swap_b32 v116, v120
	s_nop 1
	v_permlane32_swap_b32 v117, v121
	s_nop 0
	v_pk_add_f32 v[76:77], v[114:115], v[118:119]
	v_pk_add_f32 v[78:79], v[116:117], v[120:121]
	s_waitcnt lgkmcnt(0)
	v_pk_mul_f32 v[76:77], v[74:75], v[76:77] op_sel_hi:[0,1]
	v_pk_mul_f32 v[74:75], v[74:75], v[78:79] op_sel_hi:[0,1]
	s_waitcnt vmcnt(7)
	v_lshlrev_b32_e32 v78, 16, v72
	v_and_b32_e32 v79, 0xffff0000, v72
	v_lshlrev_b32_e32 v72, 16, v73
	v_and_b32_e32 v73, 0xffff0000, v73
	v_pk_fma_f32 v[72:73], v[44:45], v[74:75], v[72:73]
	v_pk_fma_f32 v[74:75], v[42:43], v[76:77], v[78:79]
	s_nop 0
	v_cvt_pk_bf16_f32 v74, v74, v75
	v_cvt_pk_bf16_f32 v75, v72, v73
	global_store_dwordx2 v[70:71], v[74:75], off
	ds_read_b32 v70, v1 offset:14344
	s_nop 1
	v_permlane32_swap_b32 v82, v86
	s_nop 1
	v_permlane32_swap_b32 v83, v87
	s_nop 1
	v_permlane32_swap_b32 v84, v88
	s_nop 1
	v_permlane32_swap_b32 v85, v89
	s_nop 0
	v_pk_add_f32 v[72:73], v[82:83], v[86:87]
	v_pk_add_f32 v[74:75], v[84:85], v[88:89]
	s_waitcnt lgkmcnt(0)
	v_pk_mul_f32 v[72:73], v[70:71], v[72:73] op_sel_hi:[0,1]
	v_pk_mul_f32 v[70:71], v[70:71], v[74:75] op_sel_hi:[0,1]
	s_waitcnt vmcnt(7)
	v_lshlrev_b32_e32 v74, 16, v68
	v_and_b32_e32 v75, 0xffff0000, v68
	v_lshlrev_b32_e32 v68, 16, v69
	v_and_b32_e32 v69, 0xffff0000, v69
	v_pk_fma_f32 v[68:69], v[44:45], v[70:71], v[68:69]
	v_pk_fma_f32 v[70:71], v[42:43], v[72:73], v[74:75]
	s_nop 0
	v_cvt_pk_bf16_f32 v70, v70, v71
	v_cvt_pk_bf16_f32 v71, v68, v69
	global_store_dwordx2 v[66:67], v[70:71], off
	ds_read_b32 v66, v1 offset:14348
	s_nop 1
	v_permlane32_swap_b32 v34, v38
	s_nop 1
	v_permlane32_swap_b32 v35, v39
	s_nop 1
	v_permlane32_swap_b32 v36, v40
	s_nop 1
	v_permlane32_swap_b32 v37, v41
	s_nop 0
	v_pk_add_f32 v[34:35], v[34:35], v[38:39]
	s_waitcnt vmcnt(7)
	v_lshlrev_b32_e32 v38, 16, v64
	s_waitcnt lgkmcnt(0)
	v_pk_mul_f32 v[34:35], v[66:67], v[34:35] op_sel_hi:[0,1]
	v_and_b32_e32 v39, 0xffff0000, v64
	v_pk_add_f32 v[36:37], v[36:37], v[40:41]
	v_pk_fma_f32 v[34:35], v[42:43], v[34:35], v[38:39]
	v_pk_mul_f32 v[36:37], v[66:67], v[36:37] op_sel_hi:[0,1]
	v_lshlrev_b32_e32 v40, 16, v65
	v_and_b32_e32 v41, 0xffff0000, v65
	v_cvt_pk_bf16_f32 v34, v34, v35
	v_pk_fma_f32 v[36:37], v[44:45], v[36:37], v[40:41]
	s_nop 0
	v_cvt_pk_bf16_f32 v35, v36, v37
	global_store_dwordx2 v[62:63], v[34:35], off
	ds_read_b32 v34, v1 offset:14352
	s_nop 1
	v_permlane32_swap_b32 v26, v30
	s_nop 1
	v_permlane32_swap_b32 v27, v31
	s_nop 1
	v_permlane32_swap_b32 v28, v32
	s_nop 1
	v_permlane32_swap_b32 v29, v33
	s_nop 0
	v_pk_add_f32 v[26:27], v[26:27], v[30:31]
	s_waitcnt vmcnt(7)
	v_lshlrev_b32_e32 v30, 16, v60
	s_waitcnt lgkmcnt(0)
	v_pk_mul_f32 v[26:27], v[34:35], v[26:27] op_sel_hi:[0,1]
	v_and_b32_e32 v31, 0xffff0000, v60
	v_pk_add_f32 v[28:29], v[28:29], v[32:33]
	v_pk_fma_f32 v[26:27], v[42:43], v[26:27], v[30:31]
	v_pk_mul_f32 v[28:29], v[34:35], v[28:29] op_sel_hi:[0,1]
	v_lshlrev_b32_e32 v32, 16, v61
	v_and_b32_e32 v33, 0xffff0000, v61
	v_cvt_pk_bf16_f32 v26, v26, v27
	v_pk_fma_f32 v[28:29], v[44:45], v[28:29], v[32:33]
	s_nop 0
	v_cvt_pk_bf16_f32 v27, v28, v29
	global_store_dwordx2 v[58:59], v[26:27], off
	ds_read_b32 v26, v1 offset:14356
	s_nop 1
	v_permlane32_swap_b32 v18, v22
	s_nop 1
	v_permlane32_swap_b32 v19, v23
	s_nop 1
	v_permlane32_swap_b32 v20, v24
	s_nop 1
	v_permlane32_swap_b32 v21, v25
	s_nop 0
	v_pk_add_f32 v[18:19], v[18:19], v[22:23]
	s_waitcnt vmcnt(7)
	v_lshlrev_b32_e32 v22, 16, v56
	s_waitcnt lgkmcnt(0)
	v_pk_mul_f32 v[18:19], v[26:27], v[18:19] op_sel_hi:[0,1]
	v_and_b32_e32 v23, 0xffff0000, v56
	v_pk_add_f32 v[20:21], v[20:21], v[24:25]
	v_pk_fma_f32 v[18:19], v[42:43], v[18:19], v[22:23]
	v_pk_mul_f32 v[20:21], v[26:27], v[20:21] op_sel_hi:[0,1]
	v_lshlrev_b32_e32 v24, 16, v57
	v_and_b32_e32 v25, 0xffff0000, v57
	v_cvt_pk_bf16_f32 v18, v18, v19
	v_pk_fma_f32 v[20:21], v[44:45], v[20:21], v[24:25]
	s_nop 0
	v_cvt_pk_bf16_f32 v19, v20, v21
	global_store_dwordx2 v[54:55], v[18:19], off
	ds_read_b32 v18, v1 offset:14360
	s_nop 1
	v_permlane32_swap_b32 v10, v14
	s_nop 1
	v_permlane32_swap_b32 v11, v15
	s_nop 1
	v_permlane32_swap_b32 v12, v16
	s_nop 1
	v_permlane32_swap_b32 v13, v17
	s_nop 0
	v_pk_add_f32 v[10:11], v[10:11], v[14:15]
	s_waitcnt vmcnt(7)
	v_lshlrev_b32_e32 v14, 16, v52
	s_waitcnt lgkmcnt(0)
	v_pk_mul_f32 v[10:11], v[18:19], v[10:11] op_sel_hi:[0,1]
	v_and_b32_e32 v15, 0xffff0000, v52
	v_pk_add_f32 v[12:13], v[12:13], v[16:17]
	v_pk_fma_f32 v[10:11], v[42:43], v[10:11], v[14:15]
	v_pk_mul_f32 v[12:13], v[18:19], v[12:13] op_sel_hi:[0,1]
	v_lshlrev_b32_e32 v16, 16, v53
	v_and_b32_e32 v17, 0xffff0000, v53
	v_cvt_pk_bf16_f32 v10, v10, v11
	v_pk_fma_f32 v[12:13], v[44:45], v[12:13], v[16:17]
	s_nop 0
	v_cvt_pk_bf16_f32 v11, v12, v13
	global_store_dwordx2 v[50:51], v[10:11], off
	ds_read_b32 v10, v1 offset:14364
	s_nop 1
	v_permlane32_swap_b32 v2, v6
	s_nop 1
	v_permlane32_swap_b32 v3, v7
	s_nop 1
	v_permlane32_swap_b32 v4, v8
	s_nop 1
	v_permlane32_swap_b32 v5, v9
	s_nop 0
	v_pk_add_f32 v[2:3], v[2:3], v[6:7]
	v_pk_add_f32 v[4:5], v[4:5], v[8:9]
	s_waitcnt lgkmcnt(0)
	v_pk_mul_f32 v[2:3], v[10:11], v[2:3] op_sel_hi:[0,1]
	s_waitcnt vmcnt(7)
	v_lshlrev_b32_e32 v6, 16, v48
	v_and_b32_e32 v7, 0xffff0000, v48
	v_pk_mul_f32 v[4:5], v[10:11], v[4:5] op_sel_hi:[0,1]
	v_lshlrev_b32_e32 v8, 16, v49
	v_and_b32_e32 v9, 0xffff0000, v49
	v_pk_fma_f32 v[2:3], v[42:43], v[2:3], v[6:7]
	v_pk_fma_f32 v[4:5], v[44:45], v[4:5], v[8:9]
	v_cvt_pk_bf16_f32 v2, v2, v3
	s_nop 0
	v_cvt_pk_bf16_f32 v3, v4, v5
	global_store_dwordx2 v[46:47], v[2:3], off
	s_cbranch_scc0 .LBB0_109
	v_mov_b32_e32 v1, v176
	s_add_i32 s0, s11, 3
	s_waitcnt vmcnt(0)
	s_mul_hi_u32 s1, s0, 0x6000
	v_lshlrev_b32_e32 v2, 4, v1
	v_ashrrev_i32_e32 v3, 2, v1
	s_mulk_i32 s0, 0x6000
	v_readlane_b32 s10, v254, 29
	v_and_b32_e32 v2, 0xf0, v2
	v_and_b32_e32 v3, -8, v3
	s_add_u32 s0, s10, s0
	v_readlane_b32 s10, v254, 30
	v_add_u32_e32 v2, v2, v3
	v_lshrrev_b32_e32 v1, 2, v1
	s_addc_u32 s1, s10, s1
	v_readlane_b32 s10, v254, 25
	v_and_or_b32 v34, v1, 4, v2
	v_readlane_b32 s11, v254, 26
	v_ashrrev_i32_e32 v35, 31, v34
	v_lshl_add_u64 v[36:37], v[34:35], 2, s[0:1]
	v_readlane_b32 s14, v254, 56
	v_readlane_b32 s15, v254, 57
	v_readlane_b32 s16, v254, 34
	s_andn2_b64 s[0:1], exec, s[10:11]
	v_readlane_b32 s12, v254, 23
	v_readlane_b32 s13, v254, 24
	s_and_b64 vcc, exec, s[10:11]
	s_cbranch_vccz .Lfn_mod
	v_mov_b32_e32 v1, 0x202d0
	ds_read_b32 v2, v1
	ds_read_b32 v3, v1 offset:4
	s_waitcnt lgkmcnt(0)
	v_readfirstlane_b32 s10, v2
	v_readfirstlane_b32 s11, v3
	s_add_u32 s10, s12, s10
	s_addc_u32 s11, s13, s11
	v_lshl_add_u64 v[38:39], v[34:35], 2, s[10:11]
	global_load_dwordx4 v[2:5], v[38:39], off
	global_load_dwordx4 v[10:13], v[38:39], off offset:1024
	global_load_dwordx4 v[18:21], v[38:39], off offset:2048
	global_load_dwordx4 v[26:29], v[38:39], off offset:3072
	v_mov_b32_e32 v6, 0
	v_mov_b32_e32 v7, 0
	v_mov_b32_e32 v8, 0
	v_mov_b32_e32 v9, 0
	v_mov_b32_e32 v14, 0
	v_mov_b32_e32 v15, 0
	v_mov_b32_e32 v16, 0
	v_mov_b32_e32 v17, 0
	v_mov_b32_e32 v22, 0
	v_mov_b32_e32 v23, 0
	v_mov_b32_e32 v24, 0
	v_mov_b32_e32 v25, 0
	v_mov_b32_e32 v30, 0
	v_mov_b32_e32 v31, 0
	v_mov_b32_e32 v32, 0
	v_mov_b32_e32 v33, 0
	s_branch .Lfn_done
.Lfn_mod:
	v_mov_b32_e32 v1, 0x20250
	ds_read_b32 v2, v1
	ds_read_b32 v3, v1 offset:4
	s_waitcnt lgkmcnt(0)
	v_readfirstlane_b32 s10, v2
	v_readfirstlane_b32 s11, v3
	s_add_u32 s10, s12, s10
	s_addc_u32 s11, s13, s11
	v_readlane_b32 s12, v254, 32
	s_lshl_b32 s12, s12, 2
	s_add_u32 s10, s10, s12
	s_addc_u32 s11, s11, 0
	v_lshl_add_u64 v[38:39], v[34:35], 2, s[10:11]
	global_load_dwordx4 v[2:5], v[38:39], off
	global_load_dwordx4 v[10:13], v[38:39], off offset:1024
	global_load_dwordx4 v[18:21], v[38:39], off offset:2048
	global_load_dwordx4 v[26:29], v[38:39], off offset:3072
	s_movk_i32 s10, 0x1000
	v_add_co_u32_e32 v38, vcc, s10, v36
	s_nop 1
	v_addc_co_u32_e32 v39, vcc, 0, v37, vcc
	global_load_dwordx4 v[6:9], v[38:39], off
	global_load_dwordx4 v[14:17], v[38:39], off offset:1024
	global_load_dwordx4 v[22:25], v[38:39], off offset:2048
	global_load_dwordx4 v[30:33], v[38:39], off offset:3072
	s_waitcnt vmcnt(0)
	v_pk_add_f32 v[8:9], v[8:9], 1.0 op_sel_hi:[1,0]
	v_pk_add_f32 v[6:7], v[6:7], 1.0 op_sel_hi:[1,0]
	v_pk_mul_f32 v[4:5], v[4:5], v[8:9]
	v_pk_mul_f32 v[2:3], v[2:3], v[6:7]
	v_pk_add_f32 v[16:17], v[16:17], 1.0 op_sel_hi:[1,0]
	v_pk_add_f32 v[14:15], v[14:15], 1.0 op_sel_hi:[1,0]
	v_pk_mul_f32 v[12:13], v[12:13], v[16:17]
	v_pk_mul_f32 v[10:11], v[10:11], v[14:15]
	v_pk_add_f32 v[24:25], v[24:25], 1.0 op_sel_hi:[1,0]
	v_pk_add_f32 v[22:23], v[22:23], 1.0 op_sel_hi:[1,0]
	v_pk_mul_f32 v[20:21], v[20:21], v[24:25]
	v_pk_mul_f32 v[18:19], v[18:19], v[22:23]
	v_pk_add_f32 v[32:33], v[32:33], 1.0 op_sel_hi:[1,0]
	v_pk_add_f32 v[30:31], v[30:31], 1.0 op_sel_hi:[1,0]
	v_pk_mul_f32 v[28:29], v[28:29], v[32:33]
	v_pk_mul_f32 v[26:27], v[26:27], v[30:31]
	global_load_dwordx4 v[6:9], v[36:37], off
	global_load_dwordx4 v[14:17], v[36:37], off offset:1024
	global_load_dwordx4 v[22:25], v[36:37], off offset:2048
	global_load_dwordx4 v[30:33], v[36:37], off offset:3072
.Lfn_done:
.LBB0_128:
	v_lshlrev_b64 v[54:55], 1, v[34:35]
	v_lshl_add_u64 v[36:37], s[22:23], 0, v[54:55]
	v_lshl_add_u64 v[38:39], v[36:37], 0, s[38:39]
	global_load_dwordx2 v[96:97], v[38:39], off
	global_load_dwordx2 v[100:101], v[38:39], off offset:512
	global_load_dwordx2 v[104:105], v[38:39], off offset:1024
	global_load_dwordx2 v[108:109], v[38:39], off offset:1536
	v_lshl_add_u64 v[38:39], v[36:37], 0, s[42:43]
	global_load_dwordx2 v[92:93], v[38:39], off
	global_load_dwordx2 v[90:91], v[38:39], off offset:512
	global_load_dwordx2 v[88:89], v[38:39], off offset:1024
	global_load_dwordx2 v[86:87], v[38:39], off offset:1536
	v_lshl_add_u64 v[38:39], v[36:37], 0, s[46:47]
	global_load_dwordx2 v[84:85], v[38:39], off
	global_load_dwordx2 v[82:83], v[38:39], off offset:512
	global_load_dwordx2 v[80:81], v[38:39], off offset:1024
	global_load_dwordx2 v[78:79], v[38:39], off offset:1536
	v_lshl_add_u64 v[38:39], v[36:37], 0, s[50:51]
	global_load_dwordx2 v[76:77], v[38:39], off
	global_load_dwordx2 v[74:75], v[38:39], off offset:512
	global_load_dwordx2 v[72:73], v[38:39], off offset:1024
	global_load_dwordx2 v[70:71], v[38:39], off offset:1536
	v_lshl_add_u64 v[38:39], v[36:37], 0, s[54:55]
	global_load_dwordx2 v[68:69], v[38:39], off
	global_load_dwordx2 v[66:67], v[38:39], off offset:512
	global_load_dwordx2 v[64:65], v[38:39], off offset:1024
	global_load_dwordx2 v[62:63], v[38:39], off offset:1536
	v_lshl_add_u64 v[38:39], v[36:37], 0, s[58:59]
	global_load_dwordx2 v[60:61], v[38:39], off
	global_load_dwordx2 v[58:59], v[38:39], off offset:512
	global_load_dwordx2 v[56:57], v[38:39], off offset:1024
	global_load_dwordx2 v[52:53], v[38:39], off offset:1536
	v_lshl_add_u64 v[38:39], v[36:37], 0, s[64:65]
	v_lshl_add_u64 v[36:37], v[36:37], 0, s[68:69]
	global_load_dwordx2 v[50:51], v[38:39], off
	global_load_dwordx2 v[48:49], v[38:39], off offset:512
	global_load_dwordx2 v[46:47], v[38:39], off offset:1024
	global_load_dwordx2 v[44:45], v[38:39], off offset:1536
	global_load_dwordx2 v[42:43], v[36:37], off
	global_load_dwordx2 v[40:41], v[36:37], off offset:512
	s_nop 0
	global_load_dwordx2 v[38:39], v[36:37], off offset:1024
	s_nop 0
	global_load_dwordx2 v[36:37], v[36:37], off offset:1536
	s_waitcnt vmcnt(31)
	v_and_b32_e32 v95, 0xffff0000, v96
	s_waitcnt vmcnt(30)
	v_and_b32_e32 v99, 0xffff0000, v100
	v_lshlrev_b32_e32 v94, 16, v96
	v_mul_f32_e32 v1, v95, v95
	v_lshlrev_b32_e32 v98, 16, v100
	v_mul_f32_e32 v102, v99, v99
	v_lshlrev_b32_e32 v96, 16, v97
	v_fmac_f32_e32 v1, v94, v94
	v_lshlrev_b32_e32 v100, 16, v101
	v_fmac_f32_e32 v102, v98, v98
	v_and_b32_e32 v97, 0xffff0000, v97
	v_fmac_f32_e32 v1, v96, v96
	v_and_b32_e32 v101, 0xffff0000, v101
	v_fmac_f32_e32 v102, v100, v100
	v_fmac_f32_e32 v1, v97, v97
	v_fmac_f32_e32 v102, v101, v101
	s_waitcnt vmcnt(29)
	v_and_b32_e32 v103, 0xffff0000, v104
	v_add_f32_e32 v1, v1, v102
	v_lshlrev_b32_e32 v102, 16, v104
	v_mul_f32_e32 v106, v103, v103
	v_lshlrev_b32_e32 v104, 16, v105
	v_fmac_f32_e32 v106, v102, v102
	v_and_b32_e32 v105, 0xffff0000, v105
	v_fmac_f32_e32 v106, v104, v104
	v_fmac_f32_e32 v106, v105, v105
	s_waitcnt vmcnt(28)
	v_and_b32_e32 v107, 0xffff0000, v108
	v_add_f32_e32 v1, v1, v106
	v_lshlrev_b32_e32 v106, 16, v108
	v_mul_f32_e32 v110, v107, v107
	v_lshlrev_b32_e32 v108, 16, v109
	v_fmac_f32_e32 v110, v106, v106
	v_and_b32_e32 v109, 0xffff0000, v109
	v_fmac_f32_e32 v110, v108, v108
	v_fmac_f32_e32 v110, v109, v109
	v_add_f32_e32 v1, v1, v110
	s_nop 1
	v_add_f32_dpp v1, v1, v1 quad_perm:[1,0,3,2] row_mask:0xf bank_mask:0xf bound_ctrl:1
	s_nop 1
	v_add_f32_dpp v1, v1, v1 quad_perm:[2,3,0,1] row_mask:0xf bank_mask:0xf bound_ctrl:1
	s_nop 1
	v_add_f32_dpp v1, v1, v1 row_half_mirror row_mask:0xf bank_mask:0xf bound_ctrl:1
	s_nop 1
	v_add_f32_dpp v1, v1, v1 row_mirror row_mask:0xf bank_mask:0xf bound_ctrl:1
	s_nop 0
	v_readlane_b32 s11, v1, 16
	v_readlane_b32 s13, v1, 48
	v_readlane_b32 s10, v1, 0
	v_readlane_b32 s12, v1, 32
	v_mov_b32_e32 v1, s11
	v_mov_b32_e32 v110, s13
	v_add_f32_e32 v1, s10, v1
	v_add_f32_e32 v110, s12, v110
	v_add_f32_e32 v1, v1, v110
	v_fmamk_f32 v1, v1, 0x3a800000, v211
	v_cmp_gt_f32_e32 vcc, s56, v1
	v_mul_f32_e32 v110, 0x4f800000, v1
	s_nop 0
	v_cndmask_b32_e32 v1, v1, v110, vcc
	v_sqrt_f32_e32 v110, v1
	s_nop 0
	v_add_u32_e32 v111, -1, v110
	v_fma_f32 v112, -v111, v110, v1
	v_cmp_ge_f32_e64 s[12:13], 0, v112
	v_add_u32_e32 v112, 1, v110
	s_nop 0
	v_cndmask_b32_e64 v111, v110, v111, s[12:13]
	v_fma_f32 v110, -v112, v110, v1
	v_cmp_lt_f32_e64 s[12:13], 0, v110
	s_nop 1
	v_cndmask_b32_e64 v110, v111, v112, s[12:13]
	v_mul_f32_e32 v111, 0x37800000, v110
	v_cndmask_b32_e32 v110, v110, v111, vcc
	v_cmp_class_f32_e32 vcc, v1, v212
	s_mov_b64 s[12:13], -1
	s_nop 0
	v_cndmask_b32_e32 v1, v110, v1, vcc
	v_div_scale_f32 v110, s[10:11], v1, v1, 1.0
	v_rcp_f32_e32 v111, v110
	v_readlane_b32 s10, v254, 25
	v_readlane_b32 s11, v254, 26
	v_fma_f32 v112, -v110, v111, 1.0
	v_fmac_f32_e32 v111, v112, v111
	v_div_scale_f32 v112, vcc, 1.0, v1, 1.0
	v_mul_f32_e32 v113, v112, v111
	v_fma_f32 v114, -v110, v113, v112
	v_fmac_f32_e32 v113, v114, v111
	v_fma_f32 v110, -v110, v113, v112
	v_div_fmas_f32 v110, v110, v111, v113
	v_div_fixup_f32 v110, v110, v1, 1.0
	s_and_b64 vcc, exec, s[10:11]
	s_cbranch_vccz .LBB0_130
	s_lshl_b64 s[10:11], s[40:41], 12
	s_add_u32 s10, s14, s10
	s_addc_u32 s11, s15, s11
	v_pk_mul_f32 v[112:113], v[110:111], v[96:97] op_sel_hi:[0,1]
	v_pk_mul_f32 v[118:119], v[110:111], v[94:95] op_sel_hi:[0,1]
	v_lshl_add_u64 v[116:117], v[34:35], 2, s[10:11]
	v_pk_mul_f32 v[114:115], v[4:5], v[112:113]
	v_pk_mul_f32 v[112:113], v[2:3], v[118:119]
	global_store_dwordx4 v[116:117], v[112:115], off
	v_pk_mul_f32 v[118:119], v[110:111], v[98:99] op_sel_hi:[0,1]
	s_mov_b64 s[12:13], 0
	v_pk_mul_f32 v[112:113], v[110:111], v[100:101] op_sel_hi:[0,1]
	v_pk_mul_f32 v[114:115], v[12:13], v[112:113]
	v_pk_mul_f32 v[112:113], v[10:11], v[118:119]
	global_store_dwordx4 v[116:117], v[112:115], off offset:1024
	v_pk_mul_f32 v[118:119], v[110:111], v[102:103] op_sel_hi:[0,1]
	s_nop 0
	v_pk_mul_f32 v[112:113], v[110:111], v[104:105] op_sel_hi:[0,1]
	v_pk_mul_f32 v[114:115], v[20:21], v[112:113]
	v_pk_mul_f32 v[112:113], v[18:19], v[118:119]
	global_store_dwordx4 v[116:117], v[112:115], off offset:2048
	v_pk_mul_f32 v[118:119], v[110:111], v[106:107] op_sel_hi:[0,1]
	s_nop 0
	v_pk_mul_f32 v[112:113], v[110:111], v[108:109] op_sel_hi:[0,1]
	v_pk_mul_f32 v[114:115], v[28:29], v[112:113]
	v_pk_mul_f32 v[112:113], v[26:27], v[118:119]
	global_store_dwordx4 v[116:117], v[112:115], off offset:3072
